# scan output O written in 16-row x 16-channel tiles so every store instruction covers 512 contiguous bytes (was 16 partial 32-byte row segments); readout reads the tiled layout
# speedup vs baseline: 1.0050x; 1.0036x over previous
; __device__ __forceinline__ int tid_of(int wave_id) { int t = wave_id * 64 + lane_id(); asm volatile("" : "+v"(t)); return t; }
; #define ATT_BAR() do { asm volatile("s_waitcnt lgkmcnt(0)" ::: "memory"); __builtin_amdgcn_s_barrier(); asm volatile("" ::: "memory"); } while (0)
; __device__ __forceinline__ void hgrn_scan(const Params& p, LAS unsigned char* lds, int chain) {
;     int tid_o = tid_of(p.wave_id);
;     const int tid = tid_o, lane = tid & 63, wave = __builtin_amdgcn_readfirstlane(tid >> 6);
;     const int li = lane & 15, g = lane >> 4, qq = li >> 2, pp = li & 3;
;     const int dir = chain / (BATCH * NHEAD), b = (chain / NHEAD) % BATCH, h = chain % NHEAD;
;     const bf16* IA = (const bf16*)(p.ws + WS_IA) + h * HD;
;     bf16* O = (bf16*)(p.ws + (dir == 0 ? WS_OF2 : WS_OB2)) + h * HD + 16 * wave + 4 * g;
;     const long ost = dir ? -(long)WA : (long)WA;
;     const unsigned char* img0 = p.ws + WS_HIMG + (size_t)chain * NCH * HIMG_BYTES;
;     f32x4 S[8];
; #pragma unroll
;     for (int i = 0; i < 8; ++i) S[i] = (f32x4){0.f, 0.f, 0.f, 0.f};
;     u32x4 rq[2][2], rk[2][2], rp[2], rd[2], rv[2][2];
;     ...
;     HS_LOAD(0, 0); HS_LOAD(1, 1);
;     HS_STORE(0, 0);
;     HS_LOAD(2, 0);
;     ATT_BAR();
; #pragma unroll 1
;     for (int c2 = 0; c2 < NCH; c2 += 2) {
.LBB0_405:
	s_or_b64 exec, exec, s[12:13]
	s_movk_i32 s12, 0x120
	v_mul_lo_u32 v46, v132, s12
	s_mov_b32 s18, 0x6542000
	s_and_b64 s[12:13], s[6:7], exec
	s_cselect_b32 s12, s18, 0x8942000
	s_add_u32 s12, s26, s12
	s_addc_u32 s21, s27, 0
	s_ashr_i32 s18, s20, 2
	s_and_b32 s18, s18, -16
	s_ashr_i32 s19, s18, 31
	s_lshl_b64 s[38:39], s[16:17], 4
	s_add_u32 s12, s12, s38
	v_lshrrev_b32_e32 v32, 2, v47
	s_addc_u32 s20, s21, s39
	s_lshl_b64 s[16:17], s[18:19], 5
	v_and_b32_e32 v52, 12, v32
	s_add_u32 s16, s12, s16
	v_mov_b32_e32 v115, 0
	s_addc_u32 s17, s20, s17
	v_lshlrev_b32_e32 v116, 1, v52
	v_mov_b32_e32 v117, v115
	s_movk_i32 s12, 0x80
	s_and_b64 s[38:39], s[6:7], exec
	s_cselect_b32 s38, 0, 0x7800
	s_sub_u32 s16, s16, s38
	s_subb_u32 s17, s17, 0
	v_and_b32_e32 v237, 15, v47
	v_sub_u32_e32 v238, 15, v237
	v_cndmask_b32_e64 v238, v238, v237, s[6:7]
	v_lshl_add_u32 v238, v238, 5, v116
	v_mov_b32_e32 v239, 0
	v_lshl_add_u64 v[44:45], s[16:17], 0, v[238:239]
	v_mov_b32_e32 v117, 0x8ff
	v_mov_b32_e32 v138, 0xff
	v_cmp_gt_i32_e32 vcc, s12, v132
	v_add_u32_e32 v34, 0x80, v132
	v_add_u32_e32 v32, 0xffffff80, v132
	v_cndmask_b32_e32 v35, v117, v138, vcc
	v_cndmask_b32_e32 v36, v32, v34, vcc
	v_mov_b32_e32 v32, s11
	v_sub_u32_e32 v34, v35, v34
	v_cndmask_b32_e64 v33, v32, 0, vcc
	v_mov_b32_e32 v32, s10
	v_mov_b32_e32 v37, s3
	v_cndmask_b32_e64 v34, v34, v36, s[6:7]
	v_cndmask_b32_e32 v32, v32, v37, vcc
	v_ashrrev_i32_e32 v35, 31, v34
	v_lshl_add_u64 v[32:33], v[32:33], 0, v[34:35]
	v_lshlrev_b64 v[32:33], 11, v[32:33]
	v_lshl_add_u64 v[32:33], s[8:9], 0, v[32:33]
	v_lshl_add_u64 v[50:51], v[32:33], 0, v[114:115]
	global_load_dwordx4 v[32:35], v[50:51], off offset:16
	global_load_dwordx4 v[36:39], v[50:51], off
	s_movk_i32 s16, 0xa0
	v_lshlrev_b32_e32 v50, 3, v47
	s_lshl_b32 s12, s18, 1
	v_mul_lo_u32 v51, v132, s16
	s_movk_i32 s16, 0x90
	s_lshl_b64 s[14:15], s[14:15], 22
	v_and_b32_e32 v49, 15, v47
	v_and_b32_e32 v50, 24, v50
	v_mul_lo_u32 v53, v132, s16
	v_lshl_add_u64 v[118:119], v[44:45], 0, s[14:15]
	s_movk_i32 s16, 0x400
	s_and_b64 s[14:15], s[6:7], exec
	v_add_u32_e32 v139, 0, v50
	v_or_b32_e32 v56, 16, v49
	v_or_b32_e32 v57, 32, v49
	v_or_b32_e32 v58, 48, v49
	s_cselect_b32 s14, s16, 0xfffffc00
	s_add_i32 s17, 0, 0x1d400
	v_add_u32_e32 v54, s12, v139
	v_bfe_u32 v47, v47, 2, 4
	v_mov_b32_e32 v120, 0
	v_mov_b32_e32 v121, 0
	s_lshl_b32 s38, s14, 4
	s_ashr_i32 s39, s14, 31
	v_mov_b32_e32 v122, s38
	v_mov_b32_e32 v123, s39
	s_lshl_b32 s38, s14, 5
	v_mov_b32_e32 v124, s38
	v_mov_b32_e32 v125, s39
	s_mul_i32 s38, s14, 48
	v_mov_b32_e32 v126, s38
	v_mov_b32_e32 v127, s39
	s_add_i32 s14, 0, 0x10e00
	s_add_i32 s15, 0, 0x1ae00
	s_add_i32 s16, 0, 0x15e00
	s_add_i32 s12, s12, s17
	s_waitcnt lgkmcnt(0)
	s_barrier
	v_mul_u32_u24_e32 v55, 0x120, v47
	v_mul_u32_u24_e32 v141, 0xa0, v47
	v_add_u32_e32 v44, s14, v51
	v_add_u32_e32 v47, s16, v48
	v_add_u32_e32 v152, s17, v46
	v_add_u32_e32 v46, s12, v50
	v_add_u32_e32 v48, s14, v50
	v_add_u32_e32 v154, 0, v51
	v_lshlrev_b32_e32 v50, 4, v132
	s_add_u32 s14, s26, s23
	v_mul_u32_u24_e32 v142, 0x90, v49
	v_lshlrev_b32_e32 v143, 2, v52
	v_mul_u32_u24_e32 v144, 0x88, v49
	v_add_u32_e32 v45, s15, v53
	v_add_u32_e32 v49, s15, v116
	v_sub_u32_e32 v50, v154, v50
	s_addc_u32 s15, s27, s22
	s_mov_b32 s13, 0
	s_movk_i32 s20, 0x8ff
	v_add_u32_e32 v140, 0, v116
	v_or_b32_e32 v145, 64, v143
	v_or_b32_e32 v146, 0x80, v143
	v_or_b32_e32 v147, 0xc0, v143
	s_movk_i32 s21, 0x100
	v_or_b32_e32 v148, 0x100, v143
	v_or_b32_e32 v149, 0x140, v143
	v_or_b32_e32 v150, 0x180, v143
	v_or_b32_e32 v151, 0x1c0, v143
	v_add_u32_e32 v153, s16, v116
	v_mul_u32_u24_e32 v155, 0x88, v56
	v_sub_u32_e32 v156, 0, v132
	v_lshl_add_u64 v[128:129], s[14:15], 0, v[40:41]
	v_lshl_add_u64 v[130:131], s[14:15], 0, v[42:43]
	s_mov_b64 s[14:15], 0
	s_movk_i32 s22, 0xff00
	s_mov_b32 s30, -2
	v_add_u32_e32 v157, v54, v55
	v_add_u32_e32 v158, v44, v113
	v_add_u32_e32 v159, v45, v113
	v_add_u32_e32 v160, v47, v113
	v_add_u32_e32 v161, v46, v55
	v_add_u32_e32 v162, v48, v141
	v_add_u32_e32 v163, v49, v142
	v_add_u32_e32 v164, v50, v113
	v_mov_b32_e32 v68, v115
	v_mov_b32_e32 v69, v115
	v_mov_b32_e32 v70, v115
	v_mov_b32_e32 v71, v115
	v_mov_b32_e32 v64, v115
	v_mov_b32_e32 v65, v115
	v_mov_b32_e32 v66, v115
	v_mov_b32_e32 v67, v115
	v_mov_b32_e32 v84, v115
	v_mov_b32_e32 v85, v115
	v_mov_b32_e32 v86, v115
	v_mov_b32_e32 v87, v115
	v_mov_b32_e32 v72, v115
	v_mov_b32_e32 v73, v115
	v_mov_b32_e32 v74, v115
	v_mov_b32_e32 v75, v115
	v_mov_b32_e32 v88, v115
	v_mov_b32_e32 v89, v115
	v_mov_b32_e32 v90, v115
	v_mov_b32_e32 v91, v115
	v_mov_b32_e32 v80, v115
	v_mov_b32_e32 v81, v115
	v_mov_b32_e32 v82, v115
	v_mov_b32_e32 v83, v115
	v_mov_b32_e32 v92, v115
	v_mov_b32_e32 v93, v115
	v_mov_b32_e32 v94, v115
	v_mov_b32_e32 v95, v115
	v_mov_b32_e32 v76, v115
	v_mov_b32_e32 v77, v115
	v_mov_b32_e32 v78, v115
	v_mov_b32_e32 v79, v115
	s_branch .LBB0_408

; __device__ __forceinline__ void phase_readout(const Params& p, int vb, int nb) {
;     ...
;         for (int u = 0; u < 2; ++u) { const int row = row0 + u * NGW; if (row < ML) { const size_t off = (size_t)row * WA + 16 * lane;
;             a[u][0] = *(const u32x4*)(OF + off); a[u][1] = *(const u32x4*)(OF + off + 8); b[u][0] = *(const u32x4*)(OB + off); b[u][1] = *(const u32x4*)(OB + off + 8);
;             gg[u][0] = *(const u32x4*)(GA + off); gg[u][1] = *(const u32x4*)(GA + off + 8); } }
.LBB0_562:
	s_ashr_i32 s49, s48, 31
	s_lshl_b64 s[12:13], s[48:49], 11
	v_lshl_or_b32 v40, v64, 1, s12
	v_mov_b32_e32 v41, s13
	s_and_b32 s100, s48, 0xfffffff0
	s_lshl_b32 s100, s100, 11
	s_and_b32 s101, s48, 15
	s_lshl_b32 s101, s101, 5
	s_or_b32 s100, s100, s101
	v_lshl_or_b32 v100, v64, 5, s100
	v_mov_b32_e32 v101, 0
	v_lshl_add_u64 v[42:43], s[4:5], 0, v[100:101]
	global_load_dwordx4 v[56:59], v[42:43], off offset:16
	global_load_dwordx4 v[48:51], v[42:43], off
	v_lshl_add_u64 v[42:43], s[8:9], 0, v[100:101]
	v_lshl_add_u64 v[68:69], s[6:7], 0, v[40:41]
	global_load_dwordx4 v[60:63], v[42:43], off offset:16
	global_load_dwordx4 v[52:55], v[42:43], off
	s_nop 0
	global_load_dwordx4 v[40:43], v[68:69], off offset:16
	global_load_dwordx4 v[44:47], v[68:69], off
	s_add_i32 s10, s48, s46
	s_cmpk_lt_i32 s10, 0x2000
	s_cselect_b64 s[14:15], -1, 0
	s_cmpk_gt_i32 s10, 0x1fff
	s_cbranch_scc1 .LBB0_564
	s_ashr_i32 s11, s10, 31
	s_lshl_b64 s[16:17], s[10:11], 11
	v_lshl_or_b32 v32, v64, 1, s16
	v_mov_b32_e32 v33, s17
	s_and_b32 s100, s10, 0xfffffff0
	s_lshl_b32 s100, s100, 11
	s_and_b32 s101, s10, 15
	s_lshl_b32 s101, s101, 5
	s_or_b32 s100, s100, s101
	v_lshl_or_b32 v102, v64, 5, s100
	v_mov_b32_e32 v103, 0
	v_lshl_add_u64 v[24:25], s[4:5], 0, v[102:103]
	v_lshl_add_u64 v[34:35], s[8:9], 0, v[102:103]
	v_lshl_add_u64 v[68:69], s[6:7], 0, v[32:33]
	global_load_dwordx4 v[16:19], v[24:25], off offset:16
	global_load_dwordx4 v[20:23], v[24:25], off
	s_nop 0
	global_load_dwordx4 v[24:27], v[34:35], off offset:16
	global_load_dwordx4 v[28:31], v[34:35], off
	s_nop 0
	global_load_dwordx4 v[32:35], v[68:69], off offset:16
	global_load_dwordx4 v[36:39], v[68:69], off
